# converter throttled to one tile in flight, tn-fastest tile order, grid==256 guard with baseline fallback; GDN DPP spacing
# speedup vs baseline: 1.0902x; 1.0070x over previous
; #define LAS __attribute__((address_space(3)))
; __device__ __forceinline__ int tidx() { int t = threadIdx.x; asm volatile("" : "+v"(t)); return t; }
;     typedef RecCfg<MIX> C;
;     const int tid = tidx(), s = tid >> 3, c4 = (tid & 7) * 4;
;     const Slot sl = slot_of<SAMPLE>(chunk, s, sg);
;     f32x4 o = *(const LAS f32x4*)(L + C::OFF_O + s * 32 + c4);
;     if constexpr (MIX == 3) o = o + *(const LAS f32x4*)(L + C::OFF_XSD + s * 32 + c4);
;     u32x2 w; w.x = pkh(o[0], o[1]); w.y = pkh(o[2], o[3]);
;     if (c4 < nv) *(u32x2*)(raw + (size_t)sl.row * DM + mixer * 256 + head * 64 + vcol0 + c4) = w;
; }
; __device__ __forceinline__ void phase_rec(const Params& p, int l, LAS unsigned char* lds) {
;     ...
;         else { rec_unit_chunked<3>(p, l, lds, sg, head, vhalf); rec_unit<1, false, true>(p, l, lds, sg, head, vhalf * 32); rec_unit<0, false, true>(p, l, lds, sg, head, vhalf * 32);
;             if (l == 0) convert_tiles(N_TILES_WIN0 + 4800 + bi * 14, N_TILES_WIN0 + 4800 + bi * 14 + 14, 1, (LAS float*)lds); }
.LBB0_220:
	s_or_b64 exec, exec, s[10:11]
	v_mov_b32_e32 v0, v202
	s_waitcnt lgkmcnt(0)
	s_barrier
	s_add_i32 s2, 0, 0x10400
	v_ashrrev_i32_e32 v1, 3, v0
	v_lshlrev_b32_e32 v0, 2, v0
	v_and_b32_e32 v6, 28, v0
	v_and_b32_e32 v0, -4, v1
	v_add_u32_e32 v0, s26, v0
	v_and_or_b32 v4, v1, 3, v0
	v_lshlrev_b32_e32 v0, 7, v1
	v_lshlrev_b32_e32 v1, 2, v6
	v_add3_u32 v0, s2, v0, v1
	ds_read_b128 v[0:3], v0
	v_ashrrev_i32_e32 v5, 31, v4
	s_mov_b32 s89, s79
	v_lshlrev_b32_e32 v16, 1, v6
	v_readlane_b32 s2, v252, 46
	s_waitcnt lgkmcnt(0)
	v_cvt_pk_f16_f32 v0, v0, v1
	v_cvt_pk_f16_f32 v1, v2, v3
	v_lshlrev_b64 v[2:3], 11, v[4:5]
	v_lshl_add_u64 v[2:3], s[8:9], 0, v[2:3]
	v_lshl_add_u64 v[2:3], v[2:3], 0, s[78:79]
	v_lshl_add_u64 v[2:3], v[2:3], 0, s[88:89]
	v_lshl_add_u64 v[2:3], v[2:3], 0, v[16:17]
	v_add_co_u32_e32 v2, vcc, 0x3500000, v2
	v_readlane_b32 s3, v252, 47
	s_nop 0
	v_addc_co_u32_e32 v3, vcc, 0, v3, vcc
	global_store_dwordx2 v[2:3], v[0:1], off
	s_barrier
	s_load_dwordx2 s[82:83], s[0:1], 0xe8
	v_readlane_b32 s60, v252, 28
	s_andn2_b64 vcc, exec, s[2:3]
	v_readlane_b32 s61, v252, 29
	s_waitcnt lgkmcnt(0)
	v_readlane_b32 s83, v252, 33
	s_mov_b32 s23, 0x41a00000
	s_mov_b32 s62, 0x3f2aaaab
	s_mov_b32 s63, 0x3f317218
	s_mov_b32 s64, 0x33800000
	s_mov_b32 s58, 0x81ff
	s_mov_b32 s66, 0x358637bd
	s_mov_b64 s[68:69], 0x1010
	s_mov_b64 s[70:71], 0x1210
	s_mov_b64 s[72:73], 0x400000
	s_mov_b64 s[54:55], 0x200
	s_mov_b64 s[56:57], 0x2000
	s_mul_i32 s59, s35, 0x84
	s_cbranch_vccnz .LBB0_256
	s_cmpk_eq_u32 s82, 0x100
	s_cbranch_scc1 .LBB0_256
	s_cmpk_gt_i32 s77, 0xff4d
	s_cselect_b64 s[10:11], -1, 0
	s_and_b64 s[2:3], s[10:11], exec
	s_mov_b64 s[2:3], s[0:1]
	s_mul_i32 s36, s77, 14
	s_cselect_b32 s4, 0xfffff2c0, 0
	s_load_dwordx2 s[2:3], s[2:3], 0xe0
	s_add_i32 s42, s36, s4
	s_addk_i32 s42, 0x1700
	s_and_b64 s[4:5], s[10:11], exec
	s_cselect_b32 s4, 0x1a80000, 0
	s_waitcnt lgkmcnt(0)
	s_add_u32 s8, s2, s4
	s_addc_u32 s9, s3, 0
	s_cmpk_gt_i32 s42, 0x43f
	s_mov_b64 s[12:13], -1
	s_cbranch_scc0 .LBB0_230
	s_cmpk_gt_u32 s42, 0x53f
	s_cbranch_scc0 .LBB0_227
	s_and_b64 s[2:3], s[10:11], exec
	s_cselect_b32 s3, 0x400000, 0
	s_cmpk_gt_u32 s42, 0x93f
	s_cbranch_scc0 .LBB0_225
	s_mov_b64 s[4:5], s[0:1]
	s_load_dwordx2 s[4:5], s[4:5], 0xc8
	s_add_i32 s2, s42, 0xfffff6c0
	s_lshl_b32 s6, s3, 2
	s_mov_b64 s[12:13], 0
	s_waitcnt lgkmcnt(0)
	s_add_u32 s6, s4, s6
	s_addc_u32 s7, s5, 0
	s_add_u32 s4, s8, 0x1280000
	s_addc_u32 s5, s9, 0
	s_and_b32 s26, s36, 62
	s_lshr_b32 s2, s2, 6

; #define LAS __attribute__((address_space(3)))
; __device__ __forceinline__ int tidx() { int t = threadIdx.x; asm volatile("" : "+v"(t)); return t; }
; __device__ __forceinline__ const float* pin(int i) { return kargs()->in[i]; }
; __device__ __forceinline__ float* pout() { return kargs()->out; }
; __device__ __forceinline__ void copy_x_rows(int r0, int n) {
;     const f32x4* xp = (const f32x4*)pin(0); const f32x4* xs = (const f32x4*)pin(1); f32x4* X = (f32x4*)(pout() + O_Y);
;     for (int i = tidx(); i < n * 256; i += 512) { const size_t e = (size_t)r0 * 256 + i;
;         X[e] = e < (size_t)TP * 256 ? xp[e] : xs[e - (size_t)TP * 256]; }
; }
; __device__ __forceinline__ void phase_rec(const Params& p, int l, LAS unsigned char* lds) {
;     ...
;         else if (mixer == 2) { rec_unit_chunked<2>(p, l, lds, sg, head, vhalf); rec_unit<2, false, true>(p, l, lds, sg, head, vhalf * 32); rec_unit<3, false, true>(p, l, lds, sg, head, vhalf * 32);
;             if (l == 0) { convert_tiles(N_TILES_WIN0 + 2560 + bi * 35, N_TILES_WIN0 + 2560 + bi * 35 + 35, 1, (LAS float*)lds); copy_x_rows((64 + bi) * 132, 132); } }
.LBB0_288:
	s_or_b64 exec, exec, s[8:9]
	v_mov_b32_e32 v0, v202
	s_waitcnt lgkmcnt(0)
	s_barrier
	s_add_i32 s2, 0, 0x14c00
	v_ashrrev_i32_e32 v1, 3, v0
	v_lshlrev_b32_e32 v0, 2, v0
	v_and_b32_e32 v10, 28, v0
	v_and_b32_e32 v0, -4, v1
	v_add_u32_e32 v0, s26, v0
	v_lshlrev_b32_e32 v4, 7, v1
	v_lshlrev_b32_e32 v5, 2, v10
	v_and_or_b32 v8, v1, 3, v0
	v_add3_u32 v0, s2, v4, v5
	v_add3_u32 v4, s29, v4, v5
	ds_read_b128 v[0:3], v0
	ds_read_b128 v[4:7], v4
	v_ashrrev_i32_e32 v9, 31, v8
	s_mov_b32 s89, s79
	v_lshlrev_b32_e32 v16, 1, v10
	v_readlane_b32 s2, v252, 46
	s_waitcnt lgkmcnt(0)
	v_pk_add_f32 v[2:3], v[2:3], v[6:7]
	v_pk_add_f32 v[0:1], v[0:1], v[4:5]
	v_readlane_b32 s3, v252, 47
	v_cvt_pk_f16_f32 v0, v0, v1
	v_cvt_pk_f16_f32 v1, v2, v3
	v_lshlrev_b64 v[2:3], 11, v[8:9]
	v_lshl_add_u64 v[2:3], s[4:5], 0, v[2:3]
	v_lshl_add_u64 v[2:3], v[2:3], 0, s[78:79]
	v_lshl_add_u64 v[2:3], v[2:3], 0, s[88:89]
	v_lshl_add_u64 v[2:3], v[2:3], 0, v[16:17]
	v_add_co_u32_e32 v2, vcc, 0x3500000, v2
	v_readlane_b32 s60, v252, 28
	s_nop 0
	v_addc_co_u32_e32 v3, vcc, 0, v3, vcc
	s_andn2_b64 vcc, exec, s[2:3]
	v_readlane_b32 s61, v252, 29
	s_mov_b32 s23, 0x41a00000
	s_mov_b32 s62, 0x3f2aaaab
	s_mov_b32 s63, 0x3f317218
	s_mov_b32 s64, 0x33800000
	s_mov_b32 s58, 0x81ff
	s_mov_b32 s66, 0x358637bd
	s_mov_b64 s[68:69], 0x1010
	s_mov_b64 s[70:71], 0x1210
	s_mov_b64 s[72:73], 0x400000
	s_mov_b64 s[54:55], 0x200
	s_mov_b64 s[56:57], 0x2000
	s_mov_b32 s59, s77
	s_mov_b32 s77, s35
	v_readlane_b32 s35, v252, 63
	global_store_dwordx2 v[2:3], v[0:1], off offset:1536
	s_barrier
	s_cbranch_vccnz .LBB0_333
	s_cmpk_lg_u32 s82, 0x100
	s_cbranch_scc1 .Lrec0_cvt2
	s_cmp_lt_u32 s77, 60
	s_cbranch_scc1 .LBB0_333
	s_branch .LBB0_329
.Lrec0_cvt2:
	s_cmp_gt_i32 s77, -8
	s_cselect_b64 s[10:11], -1, 0
	s_and_b64 s[2:3], s[10:11], exec
	s_mov_b64 s[2:3], s[0:1]
	s_mul_i32 s36, s77, 35
	s_cselect_b32 s4, 0xfffff2c0, 0
	s_load_dwordx2 s[2:3], s[2:3], 0xe0
	s_add_i32 s42, s36, s4
	s_addk_i32 s42, 0xe40
	s_and_b64 s[4:5], s[10:11], exec
	s_cselect_b32 s4, 0x1a80000, 0
	s_waitcnt lgkmcnt(0)
	s_add_u32 s8, s2, s4
	s_addc_u32 s9, s3, 0
	s_cmpk_gt_i32 s42, 0x43f
	s_mov_b64 s[12:13], -1
	s_cbranch_scc0 .LBB0_298
	s_cmpk_gt_u32 s42, 0x53f
	s_cbranch_scc0 .LBB0_295
	s_and_b64 s[2:3], s[10:11], exec
	s_cselect_b32 s3, 0x400000, 0
	s_cmpk_gt_u32 s42, 0x93f
	s_cbranch_scc0 .LBB0_293
	s_mov_b64 s[4:5], s[0:1]
	s_load_dwordx2 s[4:5], s[4:5], 0xc8
	s_add_i32 s2, s42, 0xfffff6c0
	s_lshl_b32 s6, s3, 2
	s_mov_b64 s[12:13], 0
	s_waitcnt lgkmcnt(0)
	s_add_u32 s6, s4, s6
	s_addc_u32 s7, s5, 0
	s_add_u32 s4, s8, 0x1280000
	s_addc_u32 s5, s9, 0
	s_and_b32 s26, s36, 63
	s_lshr_b32 s2, s2, 6

; #define LAS __attribute__((address_space(3)))
; __device__ __forceinline__ void phase_rec(const Params& p, int l, LAS unsigned char* lds) {
;     ...
;         if (mixer == 0) { rec_unit<0, true, false>(p, l, lds, sg, head, vhalf * 32);
;             if (l == 0) { convert_tiles(N_TILES_WIN0 + bi * 40, N_TILES_WIN0 + bi * 40 + 40, 1, (LAS float*)lds); copy_x_rows(bi * 132, 132); } }
.LBB0_355:
	s_or_b64 exec, exec, s[4:5]
	v_readlane_b32 s2, v252, 46
	v_readlane_b32 s3, v252, 47
	s_andn2_b64 vcc, exec, s[2:3]
	s_cbranch_vccnz .LBB0_402
	s_cmpk_eq_u32 s82, 0x100
	s_cbranch_scc1 .LBB0_402
	s_cmp_gt_i32 s77, 57
	s_cselect_b64 s[10:11], -1, 0
	s_and_b64 s[2:3], s[10:11], exec
	s_mov_b64 s[2:3], s[0:1]
	s_mul_i32 s25, s77, 40
	s_cselect_b32 s4, 0xfffff2c0, 0
	s_load_dwordx2 s[2:3], s[2:3], 0xe0
	s_add_i32 s42, s25, s4
	s_add_i32 s26, s42, 0x440
	s_and_b64 s[4:5], s[10:11], exec
	s_cselect_b32 s4, 0x1a80000, 0
	s_waitcnt lgkmcnt(0)
	s_add_u32 s8, s2, s4
	s_addc_u32 s9, s3, 0
	s_cmpk_gt_i32 s26, 0x43f
	s_mov_b64 s[12:13], -1
	s_cbranch_scc0 .LBB0_365
	s_cmpk_gt_u32 s26, 0x53f
	s_cbranch_scc0 .LBB0_362
	s_and_b64 s[2:3], s[10:11], exec
	s_cselect_b32 s3, 0x400000, 0
	s_cmpk_gt_u32 s26, 0x93f
	s_cbranch_scc0 .LBB0_360
	s_mov_b64 s[4:5], s[0:1]
	s_load_dwordx2 s[4:5], s[4:5], 0xc8
	s_add_i32 s2, s26, 0xfffff6c0
	s_lshl_b32 s6, s3, 2
	s_mov_b64 s[12:13], 0
	s_waitcnt lgkmcnt(0)
	s_add_u32 s6, s4, s6
	s_addc_u32 s7, s5, 0
	s_add_u32 s4, s8, 0x1280000
	s_addc_u32 s5, s9, 0
	s_and_b32 s22, s25, 56
	s_lshr_b32 s2, s2, 6

; __device__ __forceinline__ void gdn_group8(float (&S)[4], float (&pp)[16], int j0, const LAS float* L, int sbase_, int kg, int vl) {
;     typedef RecCfg<1> C;
;     f32x4 q[8], k[8]; f32x2 sc[8]; float v[8];
; #pragma unroll
;     for (int j = 0; j < 8; ++j) { const int s = sbase_ + j;
;         q[j] = *(const LAS f32x4*)(L + C::OFF_Q + s * 64 + kg * 4); k[j] = *(const LAS f32x4*)(L + C::OFF_K + s * 64 + kg * 4);
;         sc[j] = *(const LAS f32x2*)(L + C::OFF_SC + s * 4); v[j] = L[C::OFF_V + s * 32 + vl]; }
;     __builtin_amdgcn_sched_barrier(0);
;     f32x2 s0 = (f32x2){S[0], S[1]}, s1 = (f32x2){S[2], S[3]};
; #pragma unroll
;     for (int j = 0; j < 8; ++j) {
;         const f32x2 k0 = (f32x2){k[j][0], k[j][1]}, k1 = (f32x2){k[j][2], k[j][3]};
;         f32x2 r2 = s0 * k0; r2 = s1 * k1 + r2;
;         const float r = red16(r2.x + r2.y);
;         const float u = sc[j][1] * (v[j] - sc[j][0] * r);
;         const f32x2 uu = (f32x2){u, u}, aa = (f32x2){sc[j][0], sc[j][0]};
;         s0 = s0 * aa + k0 * uu; s1 = s1 * aa + k1 * uu;
;         f32x2 p2 = s0 * (f32x2){q[j][0], q[j][1]}; p2 = s1 * (f32x2){q[j][2], q[j][3]} + p2;
;         pp[j0 + j] = p2.x + p2.y;
;     }
;     S[0] = s0.x; S[1] = s0.y; S[2] = s1.x; S[3] = s1.y;
; }
; __device__ __forceinline__ void hgrn_group8(float (&S)[4], float (&pp)[16], int j0, const LAS float* L, int sbase_, int kg, int vl) {
;     typedef RecCfg<0> C;
;     f32x4 q[8], f[8]; float v[8];
; #pragma unroll
;     for (int j = 0; j < 8; ++j) { const int s = sbase_ + j;
;         q[j] = *(const LAS f32x4*)(L + C::OFF_Q + s * 64 + kg * 4); f[j] = *(const LAS f32x4*)(L + C::OFF_F + s * 64 + kg * 4);
;         v[j] = L[C::OFF_V + s * 32 + vl]; }
;     __builtin_amdgcn_sched_barrier(0);
;     f32x2 s0 = (f32x2){S[0], S[1]}, s1 = (f32x2){S[2], S[3]};
; #pragma unroll
;     for (int j = 0; j < 8; ++j) {
;         const f32x2 vv = (f32x2){v[j], v[j]};
;         s0 = (f32x2){f[j][0], f[j][1]} * (s0 - vv) + vv; s1 = (f32x2){f[j][2], f[j][3]} * (s1 - vv) + vv;
;         f32x2 p2 = s0 * (f32x2){q[j][0], q[j][1]}; p2 = s1 * (f32x2){q[j][2], q[j][3]} + p2;
;         pp[j0 + j] = p2.x + p2.y;
;     }
;     S[0] = s0.x; S[1] = s0.y; S[2] = s1.x; S[3] = s1.y;
; }
; __device__ __forceinline__ float reduce_scatter16(const float (&p)[16], int kg) {
;     const bool b3 = kg & 8, b2 = kg & 4, b1 = kg & 2, b0 = kg & 1;
.Lgdn_step_loop:
	s_waitcnt lgkmcnt(0)
	v_pk_mul_f32 v[158:159], v[10:11], v[32:33]
	v_pk_mul_f32 v[160:161], v[10:11], v[64:65] op_sel_hi:[1,0]
	v_pk_fma_f32 v[158:159], v[12:13], v[34:35], v[158:159]
	v_pk_mul_f32 v[162:163], v[12:13], v[64:65] op_sel_hi:[1,0]
	v_add_f32_e32 v168, v158, v159
	ds_read_b128 v[72:75], v172 offset:0
	ds_read_b128 v[76:79], v172 offset:16384
	v_add_f32_dpp v168, v168, v168 quad_perm:[1,0,3,2] row_mask:0xf bank_mask:0xf bound_ctrl:1
	ds_read_b128 v[80:83], v172 offset:256
	ds_read_b128 v[84:87], v172 offset:16640
	v_add_f32_dpp v168, v168, v168 quad_perm:[2,3,0,1] row_mask:0xf bank_mask:0xf bound_ctrl:1
	ds_read_b128 v[88:91], v172 offset:512
	ds_read_b128 v[92:95], v172 offset:16896
	v_add_f32_dpp v168, v168, v168 row_half_mirror row_mask:0xf bank_mask:0xf bound_ctrl:1
	ds_read_b128 v[96:99], v172 offset:768
	ds_read_b128 v[100:103], v172 offset:17152
	v_add_f32_dpp v168, v168, v168 row_mirror row_mask:0xf bank_mask:0xf bound_ctrl:1
	v_fma_f32 v170, -v64, v168, v60
	v_mul_f32_e32 v170, v65, v170
	v_pk_fma_f32 v[10:11], v[32:33], v[170:171], v[160:161] op_sel_hi:[1,0,1]
	v_pk_fma_f32 v[12:13], v[34:35], v[170:171], v[162:163] op_sel_hi:[1,0,1]
	v_pk_mul_f32 v[158:159], v[10:11], v[40:41]
	v_pk_mul_f32 v[160:161], v[10:11], v[66:67] op_sel_hi:[1,0]
	v_pk_fma_f32 v[158:159], v[12:13], v[42:43], v[158:159]
	v_pk_mul_f32 v[162:163], v[12:13], v[66:67] op_sel_hi:[1,0]
	v_add_f32_e32 v168, v158, v159
	v_pk_mul_f32 v[164:165], v[28:29], v[10:11]
	ds_read2_b32 v[104:105], v173 offset1:32
	v_add_f32_dpp v168, v168, v168 quad_perm:[1,0,3,2] row_mask:0xf bank_mask:0xf bound_ctrl:1
	v_pk_fma_f32 v[164:165], v[30:31], v[12:13], v[164:165]
	ds_read2_b32 v[106:107], v173 offset0:64 offset1:96
	v_add_f32_dpp v168, v168, v168 quad_perm:[2,3,0,1] row_mask:0xf bank_mask:0xf bound_ctrl:1
	v_add_f32_e32 v116, v164, v165
	ds_read2_b64 v[108:111], v174 offset1:2
	v_add_f32_dpp v168, v168, v168 row_half_mirror row_mask:0xf bank_mask:0xf bound_ctrl:1
	ds_read2_b64 v[112:115], v174 offset0:4 offset1:6
	v_add_u32_e32 v172, 0x400, v172
	v_add_f32_dpp v168, v168, v168 row_mirror row_mask:0xf bank_mask:0xf bound_ctrl:1
	v_fma_f32 v170, -v66, v168, v61
	v_mul_f32_e32 v170, v67, v170
	v_pk_fma_f32 v[10:11], v[40:41], v[170:171], v[160:161] op_sel_hi:[1,0,1]
	v_pk_fma_f32 v[12:13], v[42:43], v[170:171], v[162:163] op_sel_hi:[1,0,1]
	v_pk_mul_f32 v[158:159], v[10:11], v[48:49]
	v_pk_mul_f32 v[160:161], v[10:11], v[68:69] op_sel_hi:[1,0]
	v_pk_fma_f32 v[158:159], v[12:13], v[50:51], v[158:159]
	v_pk_mul_f32 v[162:163], v[12:13], v[68:69] op_sel_hi:[1,0]
	v_add_f32_e32 v168, v158, v159
	v_pk_mul_f32 v[166:167], v[36:37], v[10:11]
	v_add_u32_e32 v173, 0x200, v173
	v_add_f32_dpp v168, v168, v168 quad_perm:[1,0,3,2] row_mask:0xf bank_mask:0xf bound_ctrl:1
	v_pk_fma_f32 v[166:167], v[38:39], v[12:13], v[166:167]
	v_add_u32_e32 v174, 64, v174
	v_add_f32_dpp v168, v168, v168 quad_perm:[2,3,0,1] row_mask:0xf bank_mask:0xf bound_ctrl:1
	v_add_f32_e32 v117, v166, v167
	v_add_f32_dpp v140, v116, v116 row_mirror row_mask:0xf bank_mask:0x3 bound_ctrl:1
	v_add_f32_dpp v168, v168, v168 row_half_mirror row_mask:0xf bank_mask:0xf bound_ctrl:1
	s_add_i32 s8, s8, -1
	v_add_f32_dpp v140, v117, v117 row_mirror row_mask:0xf bank_mask:0xc bound_ctrl:1
	v_add_f32_dpp v168, v168, v168 row_mirror row_mask:0xf bank_mask:0xf bound_ctrl:1
	v_fma_f32 v170, -v68, v168, v62
	v_mul_f32_e32 v170, v69, v170
	v_pk_fma_f32 v[10:11], v[48:49], v[170:171], v[160:161] op_sel_hi:[1,0,1]
	v_pk_fma_f32 v[12:13], v[50:51], v[170:171], v[162:163] op_sel_hi:[1,0,1]
	v_pk_mul_f32 v[158:159], v[10:11], v[56:57]
	v_pk_mul_f32 v[160:161], v[10:11], v[70:71] op_sel_hi:[1,0]
	v_pk_fma_f32 v[158:159], v[12:13], v[58:59], v[158:159]
	v_pk_mul_f32 v[162:163], v[12:13], v[70:71] op_sel_hi:[1,0]
	v_add_f32_e32 v168, v158, v159
	v_pk_mul_f32 v[164:165], v[44:45], v[10:11]
	v_add_f32_dpp v148, v140, v140 row_half_mirror row_mask:0xf bank_mask:0x5 bound_ctrl:1
	v_add_f32_dpp v168, v168, v168 quad_perm:[1,0,3,2] row_mask:0xf bank_mask:0xf bound_ctrl:1
	v_pk_fma_f32 v[164:165], v[46:47], v[12:13], v[164:165]
	s_nop 0
	v_add_f32_dpp v168, v168, v168 quad_perm:[2,3,0,1] row_mask:0xf bank_mask:0xf bound_ctrl:1
	v_add_f32_e32 v118, v164, v165
	s_nop 0
	v_add_f32_dpp v168, v168, v168 row_half_mirror row_mask:0xf bank_mask:0xf bound_ctrl:1
	v_add_f32_dpp v141, v118, v118 row_mirror row_mask:0xf bank_mask:0x3 bound_ctrl:1
	s_nop 0
	v_add_f32_dpp v168, v168, v168 row_mirror row_mask:0xf bank_mask:0xf bound_ctrl:1
	v_fma_f32 v170, -v70, v168, v63
	v_mul_f32_e32 v170, v71, v170
	v_pk_fma_f32 v[10:11], v[56:57], v[170:171], v[160:161] op_sel_hi:[1,0,1]
	v_pk_fma_f32 v[12:13], v[58:59], v[170:171], v[162:163] op_sel_hi:[1,0,1]
	s_waitcnt lgkmcnt(0)
; __device__ __forceinline__ void gdn_group8(float (&S)[4], float (&pp)[16], int j0, const LAS float* L, int sbase_, int kg, int vl) {
;     typedef RecCfg<1> C;
;     f32x4 q[8], k[8]; f32x2 sc[8]; float v[8];
; #pragma unroll
;     for (int j = 0; j < 8; ++j) { const int s = sbase_ + j;
;         q[j] = *(const LAS f32x4*)(L + C::OFF_Q + s * 64 + kg * 4); k[j] = *(const LAS f32x4*)(L + C::OFF_K + s * 64 + kg * 4);
;         sc[j] = *(const LAS f32x2*)(L + C::OFF_SC + s * 4); v[j] = L[C::OFF_V + s * 32 + vl]; }
;     __builtin_amdgcn_sched_barrier(0);
;     f32x2 s0 = (f32x2){S[0], S[1]}, s1 = (f32x2){S[2], S[3]};
; #pragma unroll
;     for (int j = 0; j < 8; ++j) {
;         const f32x2 k0 = (f32x2){k[j][0], k[j][1]}, k1 = (f32x2){k[j][2], k[j][3]};
;         f32x2 r2 = s0 * k0; r2 = s1 * k1 + r2;
;         const float r = red16(r2.x + r2.y);
;         const float u = sc[j][1] * (v[j] - sc[j][0] * r);
;         const f32x2 uu = (f32x2){u, u}, aa = (f32x2){sc[j][0], sc[j][0]};
;         s0 = s0 * aa + k0 * uu; s1 = s1 * aa + k1 * uu;
;         f32x2 p2 = s0 * (f32x2){q[j][0], q[j][1]}; p2 = s1 * (f32x2){q[j][2], q[j][3]} + p2;
;         pp[j0 + j] = p2.x + p2.y;
;     }
;     S[0] = s0.x; S[1] = s0.y; S[2] = s1.x; S[3] = s1.y;
; }
; __device__ __forceinline__ void hgrn_group8(float (&S)[4], float (&pp)[16], int j0, const LAS float* L, int sbase_, int kg, int vl) {
;     typedef RecCfg<0> C;
;     f32x4 q[8], f[8]; float v[8];
; #pragma unroll
;     for (int j = 0; j < 8; ++j) { const int s = sbase_ + j;
;         q[j] = *(const LAS f32x4*)(L + C::OFF_Q + s * 64 + kg * 4); f[j] = *(const LAS f32x4*)(L + C::OFF_F + s * 64 + kg * 4);
;         v[j] = L[C::OFF_V + s * 32 + vl]; }
;     __builtin_amdgcn_sched_barrier(0);
;     f32x2 s0 = (f32x2){S[0], S[1]}, s1 = (f32x2){S[2], S[3]};
; #pragma unroll
;     for (int j = 0; j < 8; ++j) {
;         const f32x2 vv = (f32x2){v[j], v[j]};
;         s0 = (f32x2){f[j][0], f[j][1]} * (s0 - vv) + vv; s1 = (f32x2){f[j][2], f[j][3]} * (s1 - vv) + vv;
;         f32x2 p2 = s0 * (f32x2){q[j][0], q[j][1]}; p2 = s1 * (f32x2){q[j][2], q[j][3]} + p2;
;         pp[j0 + j] = p2.x + p2.y;
;     }
;     S[0] = s0.x; S[1] = s0.y; S[2] = s1.x; S[3] = s1.y;
; }
; __device__ __forceinline__ float reduce_scatter16(const float (&p)[16], int kg) {
;     const bool b3 = kg & 8, b2 = kg & 4, b1 = kg & 2, b0 = kg & 1;
	v_pk_mul_f32 v[158:159], v[10:11], v[76:77]
	v_pk_mul_f32 v[160:161], v[10:11], v[108:109] op_sel_hi:[1,0]
	v_pk_fma_f32 v[158:159], v[12:13], v[78:79], v[158:159]
	v_pk_mul_f32 v[162:163], v[12:13], v[108:109] op_sel_hi:[1,0]
	v_add_f32_e32 v168, v158, v159
	v_pk_mul_f32 v[166:167], v[52:53], v[10:11]
	s_nop 0
	v_add_f32_dpp v168, v168, v168 quad_perm:[1,0,3,2] row_mask:0xf bank_mask:0xf bound_ctrl:1
	v_pk_fma_f32 v[166:167], v[54:55], v[12:13], v[166:167]
	ds_read_b128 v[28:31], v172 offset:0
	v_add_f32_dpp v168, v168, v168 quad_perm:[2,3,0,1] row_mask:0xf bank_mask:0xf bound_ctrl:1
	v_add_f32_e32 v119, v166, v167
	ds_read_b128 v[32:35], v172 offset:16384
	v_add_f32_dpp v168, v168, v168 row_half_mirror row_mask:0xf bank_mask:0xf bound_ctrl:1
	ds_read_b128 v[36:39], v172 offset:256
	ds_read_b128 v[40:43], v172 offset:16640
	v_add_f32_dpp v168, v168, v168 row_mirror row_mask:0xf bank_mask:0xf bound_ctrl:1
	v_fma_f32 v170, -v108, v168, v104
	v_mul_f32_e32 v170, v109, v170
	v_pk_fma_f32 v[10:11], v[76:77], v[170:171], v[160:161] op_sel_hi:[1,0,1]
	v_pk_fma_f32 v[12:13], v[78:79], v[170:171], v[162:163] op_sel_hi:[1,0,1]
	v_pk_mul_f32 v[158:159], v[10:11], v[84:85]
	v_pk_mul_f32 v[160:161], v[10:11], v[110:111] op_sel_hi:[1,0]
	v_pk_fma_f32 v[158:159], v[12:13], v[86:87], v[158:159]
	v_pk_mul_f32 v[162:163], v[12:13], v[110:111] op_sel_hi:[1,0]
	v_add_f32_e32 v168, v158, v159
	v_pk_mul_f32 v[164:165], v[72:73], v[10:11]
	ds_read_b128 v[44:47], v172 offset:512
	v_add_f32_dpp v168, v168, v168 quad_perm:[1,0,3,2] row_mask:0xf bank_mask:0xf bound_ctrl:1
	v_pk_fma_f32 v[164:165], v[74:75], v[12:13], v[164:165]
	ds_read_b128 v[48:51], v172 offset:16896
	v_add_f32_dpp v168, v168, v168 quad_perm:[2,3,0,1] row_mask:0xf bank_mask:0xf bound_ctrl:1
	v_add_f32_e32 v120, v164, v165
	ds_read_b128 v[52:55], v172 offset:768
	v_add_f32_dpp v168, v168, v168 row_half_mirror row_mask:0xf bank_mask:0xf bound_ctrl:1
	ds_read_b128 v[56:59], v172 offset:17152
	ds_read2_b32 v[60:61], v173 offset1:32
	v_add_f32_dpp v168, v168, v168 row_mirror row_mask:0xf bank_mask:0xf bound_ctrl:1
	v_fma_f32 v170, -v110, v168, v105
	v_mul_f32_e32 v170, v111, v170
	v_pk_fma_f32 v[10:11], v[84:85], v[170:171], v[160:161] op_sel_hi:[1,0,1]
	v_pk_fma_f32 v[12:13], v[86:87], v[170:171], v[162:163] op_sel_hi:[1,0,1]
	v_pk_mul_f32 v[158:159], v[10:11], v[92:93]
	v_pk_mul_f32 v[160:161], v[10:11], v[112:113] op_sel_hi:[1,0]
	v_pk_fma_f32 v[158:159], v[12:13], v[94:95], v[158:159]
	v_pk_mul_f32 v[162:163], v[12:13], v[112:113] op_sel_hi:[1,0]
	v_add_f32_e32 v168, v158, v159
	v_pk_mul_f32 v[166:167], v[80:81], v[10:11]
	ds_read2_b32 v[62:63], v173 offset0:64 offset1:96
	v_add_f32_dpp v168, v168, v168 quad_perm:[1,0,3,2] row_mask:0xf bank_mask:0xf bound_ctrl:1
	v_pk_fma_f32 v[166:167], v[82:83], v[12:13], v[166:167]
	ds_read2_b64 v[64:67], v174 offset1:2
	v_add_f32_dpp v168, v168, v168 quad_perm:[2,3,0,1] row_mask:0xf bank_mask:0xf bound_ctrl:1
	v_add_f32_e32 v121, v166, v167
	ds_read2_b64 v[68:71], v174 offset0:4 offset1:6
	v_add_f32_dpp v168, v168, v168 row_half_mirror row_mask:0xf bank_mask:0xf bound_ctrl:1
	v_add_u32_e32 v172, 0x400, v172
	v_add_u32_e32 v173, 0x200, v173
	v_add_f32_dpp v168, v168, v168 row_mirror row_mask:0xf bank_mask:0xf bound_ctrl:1
	v_fma_f32 v170, -v112, v168, v106
	v_mul_f32_e32 v170, v113, v170
	v_pk_fma_f32 v[10:11], v[92:93], v[170:171], v[160:161] op_sel_hi:[1,0,1]
	v_pk_fma_f32 v[12:13], v[94:95], v[170:171], v[162:163] op_sel_hi:[1,0,1]
	v_pk_mul_f32 v[158:159], v[10:11], v[100:101]
	v_pk_mul_f32 v[160:161], v[10:11], v[114:115] op_sel_hi:[1,0]
	v_pk_fma_f32 v[158:159], v[12:13], v[102:103], v[158:159]
	v_pk_mul_f32 v[162:163], v[12:13], v[114:115] op_sel_hi:[1,0]
	v_add_f32_e32 v168, v158, v159
	v_pk_mul_f32 v[164:165], v[88:89], v[10:11]
	v_add_u32_e32 v174, 64, v174
	v_add_f32_dpp v168, v168, v168 quad_perm:[1,0,3,2] row_mask:0xf bank_mask:0xf bound_ctrl:1
	v_pk_fma_f32 v[164:165], v[90:91], v[12:13], v[164:165]
	v_add_f32_dpp v142, v120, v120 row_mirror row_mask:0xf bank_mask:0x3 bound_ctrl:1
	v_add_f32_dpp v168, v168, v168 quad_perm:[2,3,0,1] row_mask:0xf bank_mask:0xf bound_ctrl:1
	v_add_f32_e32 v122, v164, v165
	v_add_f32_dpp v142, v121, v121 row_mirror row_mask:0xf bank_mask:0xc bound_ctrl:1
	v_add_f32_dpp v168, v168, v168 row_half_mirror row_mask:0xf bank_mask:0xf bound_ctrl:1
	v_add_f32_dpp v143, v122, v122 row_mirror row_mask:0xf bank_mask:0x3 bound_ctrl:1
	v_add_f32_dpp v141, v119, v119 row_mirror row_mask:0xf bank_mask:0xc bound_ctrl:1
	v_add_f32_dpp v168, v168, v168 row_mirror row_mask:0xf bank_mask:0xf bound_ctrl:1
	v_fma_f32 v170, -v114, v168, v107
	v_mul_f32_e32 v170, v115, v170
	v_pk_fma_f32 v[10:11], v[100:101], v[170:171], v[160:161] op_sel_hi:[1,0,1]
	v_pk_fma_f32 v[12:13], v[102:103], v[170:171], v[162:163] op_sel_hi:[1,0,1]
	s_waitcnt lgkmcnt(0)
; __device__ __forceinline__ void gdn_group8(float (&S)[4], float (&pp)[16], int j0, const LAS float* L, int sbase_, int kg, int vl) {
;     typedef RecCfg<1> C;
;     f32x4 q[8], k[8]; f32x2 sc[8]; float v[8];
; #pragma unroll
;     for (int j = 0; j < 8; ++j) { const int s = sbase_ + j;
;         q[j] = *(const LAS f32x4*)(L + C::OFF_Q + s * 64 + kg * 4); k[j] = *(const LAS f32x4*)(L + C::OFF_K + s * 64 + kg * 4);
;         sc[j] = *(const LAS f32x2*)(L + C::OFF_SC + s * 4); v[j] = L[C::OFF_V + s * 32 + vl]; }
;     __builtin_amdgcn_sched_barrier(0);
;     f32x2 s0 = (f32x2){S[0], S[1]}, s1 = (f32x2){S[2], S[3]};
; #pragma unroll
;     for (int j = 0; j < 8; ++j) {
;         const f32x2 k0 = (f32x2){k[j][0], k[j][1]}, k1 = (f32x2){k[j][2], k[j][3]};
;         f32x2 r2 = s0 * k0; r2 = s1 * k1 + r2;
;         const float r = red16(r2.x + r2.y);
;         const float u = sc[j][1] * (v[j] - sc[j][0] * r);
;         const f32x2 uu = (f32x2){u, u}, aa = (f32x2){sc[j][0], sc[j][0]};
;         s0 = s0 * aa + k0 * uu; s1 = s1 * aa + k1 * uu;
;         f32x2 p2 = s0 * (f32x2){q[j][0], q[j][1]}; p2 = s1 * (f32x2){q[j][2], q[j][3]} + p2;
;         pp[j0 + j] = p2.x + p2.y;
;     }
;     S[0] = s0.x; S[1] = s0.y; S[2] = s1.x; S[3] = s1.y;
; }
; __device__ __forceinline__ void hgrn_group8(float (&S)[4], float (&pp)[16], int j0, const LAS float* L, int sbase_, int kg, int vl) {
;     typedef RecCfg<0> C;
;     f32x4 q[8], f[8]; float v[8];
; #pragma unroll
;     for (int j = 0; j < 8; ++j) { const int s = sbase_ + j;
;         q[j] = *(const LAS f32x4*)(L + C::OFF_Q + s * 64 + kg * 4); f[j] = *(const LAS f32x4*)(L + C::OFF_F + s * 64 + kg * 4);
;         v[j] = L[C::OFF_V + s * 32 + vl]; }
;     __builtin_amdgcn_sched_barrier(0);
;     f32x2 s0 = (f32x2){S[0], S[1]}, s1 = (f32x2){S[2], S[3]};
; #pragma unroll
;     for (int j = 0; j < 8; ++j) {
;         const f32x2 vv = (f32x2){v[j], v[j]};
;         s0 = (f32x2){f[j][0], f[j][1]} * (s0 - vv) + vv; s1 = (f32x2){f[j][2], f[j][3]} * (s1 - vv) + vv;
;         f32x2 p2 = s0 * (f32x2){q[j][0], q[j][1]}; p2 = s1 * (f32x2){q[j][2], q[j][3]} + p2;
;         pp[j0 + j] = p2.x + p2.y;
;     }
;     S[0] = s0.x; S[1] = s0.y; S[2] = s1.x; S[3] = s1.y;
; }
; __device__ __forceinline__ float reduce_scatter16(const float (&p)[16], int kg) {
;     const bool b3 = kg & 8, b2 = kg & 4, b1 = kg & 2, b0 = kg & 1;
	v_pk_mul_f32 v[158:159], v[10:11], v[32:33]
	v_pk_mul_f32 v[160:161], v[10:11], v[64:65] op_sel_hi:[1,0]
	v_pk_fma_f32 v[158:159], v[12:13], v[34:35], v[158:159]
	v_pk_mul_f32 v[162:163], v[12:13], v[64:65] op_sel_hi:[1,0]
	v_add_f32_e32 v168, v158, v159
	v_pk_mul_f32 v[166:167], v[96:97], v[10:11]
	v_add_f32_dpp v149, v142, v142 row_half_mirror row_mask:0xf bank_mask:0x5 bound_ctrl:1
	v_add_f32_dpp v168, v168, v168 quad_perm:[1,0,3,2] row_mask:0xf bank_mask:0xf bound_ctrl:1
	v_pk_fma_f32 v[166:167], v[98:99], v[12:13], v[166:167]
	ds_read_b128 v[72:75], v172 offset:0
	v_add_f32_dpp v168, v168, v168 quad_perm:[2,3,0,1] row_mask:0xf bank_mask:0xf bound_ctrl:1
	v_add_f32_e32 v123, v166, v167
	ds_read_b128 v[76:79], v172 offset:16384
	v_add_f32_dpp v168, v168, v168 row_half_mirror row_mask:0xf bank_mask:0xf bound_ctrl:1
	ds_read_b128 v[80:83], v172 offset:256
	ds_read_b128 v[84:87], v172 offset:16640
	v_add_f32_dpp v168, v168, v168 row_mirror row_mask:0xf bank_mask:0xf bound_ctrl:1
	v_fma_f32 v170, -v64, v168, v60
	v_mul_f32_e32 v170, v65, v170
	v_pk_fma_f32 v[10:11], v[32:33], v[170:171], v[160:161] op_sel_hi:[1,0,1]
	v_pk_fma_f32 v[12:13], v[34:35], v[170:171], v[162:163] op_sel_hi:[1,0,1]
	v_pk_mul_f32 v[158:159], v[10:11], v[40:41]
	v_pk_mul_f32 v[160:161], v[10:11], v[66:67] op_sel_hi:[1,0]
	v_pk_fma_f32 v[158:159], v[12:13], v[42:43], v[158:159]
	v_pk_mul_f32 v[162:163], v[12:13], v[66:67] op_sel_hi:[1,0]
	v_add_f32_e32 v168, v158, v159
	v_pk_mul_f32 v[164:165], v[28:29], v[10:11]
	ds_read_b128 v[88:91], v172 offset:512
	v_add_f32_dpp v168, v168, v168 quad_perm:[1,0,3,2] row_mask:0xf bank_mask:0xf bound_ctrl:1
	v_pk_fma_f32 v[164:165], v[30:31], v[12:13], v[164:165]
	ds_read_b128 v[92:95], v172 offset:16896
	v_add_f32_dpp v168, v168, v168 quad_perm:[2,3,0,1] row_mask:0xf bank_mask:0xf bound_ctrl:1
	v_add_f32_e32 v124, v164, v165
	ds_read_b128 v[96:99], v172 offset:768
	v_add_f32_dpp v168, v168, v168 row_half_mirror row_mask:0xf bank_mask:0xf bound_ctrl:1
	ds_read_b128 v[100:103], v172 offset:17152
	ds_read2_b32 v[104:105], v173 offset1:32
	v_add_f32_dpp v168, v168, v168 row_mirror row_mask:0xf bank_mask:0xf bound_ctrl:1
	v_fma_f32 v170, -v66, v168, v61
	v_mul_f32_e32 v170, v67, v170
	v_pk_fma_f32 v[10:11], v[40:41], v[170:171], v[160:161] op_sel_hi:[1,0,1]
	v_pk_fma_f32 v[12:13], v[42:43], v[170:171], v[162:163] op_sel_hi:[1,0,1]
	v_pk_mul_f32 v[158:159], v[10:11], v[48:49]
	v_pk_mul_f32 v[160:161], v[10:11], v[68:69] op_sel_hi:[1,0]
	v_pk_fma_f32 v[158:159], v[12:13], v[50:51], v[158:159]
	v_pk_mul_f32 v[162:163], v[12:13], v[68:69] op_sel_hi:[1,0]
	v_add_f32_e32 v168, v158, v159
	v_pk_mul_f32 v[166:167], v[36:37], v[10:11]
	ds_read2_b32 v[106:107], v173 offset0:64 offset1:96
	v_add_f32_dpp v168, v168, v168 quad_perm:[1,0,3,2] row_mask:0xf bank_mask:0xf bound_ctrl:1
	v_pk_fma_f32 v[166:167], v[38:39], v[12:13], v[166:167]
	ds_read2_b64 v[108:111], v174 offset1:2
	v_add_f32_dpp v168, v168, v168 quad_perm:[2,3,0,1] row_mask:0xf bank_mask:0xf bound_ctrl:1
	v_add_f32_e32 v125, v166, v167
	ds_read2_b64 v[112:115], v174 offset0:4 offset1:6
	v_add_f32_dpp v168, v168, v168 row_half_mirror row_mask:0xf bank_mask:0xf bound_ctrl:1
	v_add_u32_e32 v172, 0x400, v172
	v_add_u32_e32 v173, 0x200, v173
	v_add_f32_dpp v168, v168, v168 row_mirror row_mask:0xf bank_mask:0xf bound_ctrl:1
	v_fma_f32 v170, -v68, v168, v62
	v_mul_f32_e32 v170, v69, v170
	v_pk_fma_f32 v[10:11], v[48:49], v[170:171], v[160:161] op_sel_hi:[1,0,1]
	v_pk_fma_f32 v[12:13], v[50:51], v[170:171], v[162:163] op_sel_hi:[1,0,1]
	v_pk_mul_f32 v[158:159], v[10:11], v[56:57]
	v_pk_mul_f32 v[160:161], v[10:11], v[70:71] op_sel_hi:[1,0]
	v_pk_fma_f32 v[158:159], v[12:13], v[58:59], v[158:159]
	v_pk_mul_f32 v[162:163], v[12:13], v[70:71] op_sel_hi:[1,0]
	v_add_f32_e32 v168, v158, v159
	v_pk_mul_f32 v[164:165], v[44:45], v[10:11]
	v_add_u32_e32 v174, 64, v174
	v_add_f32_dpp v168, v168, v168 quad_perm:[1,0,3,2] row_mask:0xf bank_mask:0xf bound_ctrl:1
	v_pk_fma_f32 v[164:165], v[46:47], v[12:13], v[164:165]
	v_add_f32_dpp v144, v124, v124 row_mirror row_mask:0xf bank_mask:0x3 bound_ctrl:1
	v_add_f32_dpp v168, v168, v168 quad_perm:[2,3,0,1] row_mask:0xf bank_mask:0xf bound_ctrl:1
	v_add_f32_e32 v126, v164, v165
	v_add_f32_dpp v143, v123, v123 row_mirror row_mask:0xf bank_mask:0xc bound_ctrl:1
	v_add_f32_dpp v168, v168, v168 row_half_mirror row_mask:0xf bank_mask:0xf bound_ctrl:1
	v_add_f32_dpp v144, v125, v125 row_mirror row_mask:0xf bank_mask:0xc bound_ctrl:1
	v_add_f32_dpp v145, v126, v126 row_mirror row_mask:0xf bank_mask:0x3 bound_ctrl:1
	v_add_f32_dpp v168, v168, v168 row_mirror row_mask:0xf bank_mask:0xf bound_ctrl:1
	v_fma_f32 v170, -v70, v168, v63
	v_mul_f32_e32 v170, v71, v170
	v_pk_fma_f32 v[10:11], v[56:57], v[170:171], v[160:161] op_sel_hi:[1,0,1]
	v_pk_fma_f32 v[12:13], v[58:59], v[170:171], v[162:163] op_sel_hi:[1,0,1]
	s_waitcnt lgkmcnt(0)
; __device__ __forceinline__ void gdn_group8(float (&S)[4], float (&pp)[16], int j0, const LAS float* L, int sbase_, int kg, int vl) {
;     typedef RecCfg<1> C;
;     f32x4 q[8], k[8]; f32x2 sc[8]; float v[8];
; #pragma unroll
;     for (int j = 0; j < 8; ++j) { const int s = sbase_ + j;
;         q[j] = *(const LAS f32x4*)(L + C::OFF_Q + s * 64 + kg * 4); k[j] = *(const LAS f32x4*)(L + C::OFF_K + s * 64 + kg * 4);
;         sc[j] = *(const LAS f32x2*)(L + C::OFF_SC + s * 4); v[j] = L[C::OFF_V + s * 32 + vl]; }
;     __builtin_amdgcn_sched_barrier(0);
;     f32x2 s0 = (f32x2){S[0], S[1]}, s1 = (f32x2){S[2], S[3]};
; #pragma unroll
;     for (int j = 0; j < 8; ++j) {
;         const f32x2 k0 = (f32x2){k[j][0], k[j][1]}, k1 = (f32x2){k[j][2], k[j][3]};
;         f32x2 r2 = s0 * k0; r2 = s1 * k1 + r2;
;         const float r = red16(r2.x + r2.y);
;         const float u = sc[j][1] * (v[j] - sc[j][0] * r);
;         const f32x2 uu = (f32x2){u, u}, aa = (f32x2){sc[j][0], sc[j][0]};
;         s0 = s0 * aa + k0 * uu; s1 = s1 * aa + k1 * uu;
;         f32x2 p2 = s0 * (f32x2){q[j][0], q[j][1]}; p2 = s1 * (f32x2){q[j][2], q[j][3]} + p2;
;         pp[j0 + j] = p2.x + p2.y;
;     }
;     S[0] = s0.x; S[1] = s0.y; S[2] = s1.x; S[3] = s1.y;
; }
; __device__ __forceinline__ void hgrn_group8(float (&S)[4], float (&pp)[16], int j0, const LAS float* L, int sbase_, int kg, int vl) {
;     typedef RecCfg<0> C;
;     f32x4 q[8], f[8]; float v[8];
; #pragma unroll
;     for (int j = 0; j < 8; ++j) { const int s = sbase_ + j;
;         q[j] = *(const LAS f32x4*)(L + C::OFF_Q + s * 64 + kg * 4); f[j] = *(const LAS f32x4*)(L + C::OFF_F + s * 64 + kg * 4);
;         v[j] = L[C::OFF_V + s * 32 + vl]; }
;     __builtin_amdgcn_sched_barrier(0);
;     f32x2 s0 = (f32x2){S[0], S[1]}, s1 = (f32x2){S[2], S[3]};
; #pragma unroll
;     for (int j = 0; j < 8; ++j) {
;         const f32x2 vv = (f32x2){v[j], v[j]};
;         s0 = (f32x2){f[j][0], f[j][1]} * (s0 - vv) + vv; s1 = (f32x2){f[j][2], f[j][3]} * (s1 - vv) + vv;
;         f32x2 p2 = s0 * (f32x2){q[j][0], q[j][1]}; p2 = s1 * (f32x2){q[j][2], q[j][3]} + p2;
;         pp[j0 + j] = p2.x + p2.y;
;     }
;     S[0] = s0.x; S[1] = s0.y; S[2] = s1.x; S[3] = s1.y;
; }
; __device__ __forceinline__ float reduce_scatter16(const float (&p)[16], int kg) {
;     const bool b3 = kg & 8, b2 = kg & 4, b1 = kg & 2, b0 = kg & 1;
	v_pk_mul_f32 v[158:159], v[10:11], v[76:77]
	v_pk_mul_f32 v[160:161], v[10:11], v[108:109] op_sel_hi:[1,0]
	v_pk_fma_f32 v[158:159], v[12:13], v[78:79], v[158:159]
	v_pk_mul_f32 v[162:163], v[12:13], v[108:109] op_sel_hi:[1,0]
	v_add_f32_e32 v168, v158, v159
	v_pk_mul_f32 v[166:167], v[52:53], v[10:11]
	v_add_f32_dpp v148, v141, v141 row_half_mirror row_mask:0xf bank_mask:0xa bound_ctrl:1
	v_add_f32_dpp v168, v168, v168 quad_perm:[1,0,3,2] row_mask:0xf bank_mask:0xf bound_ctrl:1
	v_pk_fma_f32 v[166:167], v[54:55], v[12:13], v[166:167]
	ds_read_b128 v[28:31], v172 offset:0
	v_add_f32_dpp v168, v168, v168 quad_perm:[2,3,0,1] row_mask:0xf bank_mask:0xf bound_ctrl:1
	v_add_f32_e32 v127, v166, v167
	ds_read_b128 v[32:35], v172 offset:16384
	v_add_f32_dpp v168, v168, v168 row_half_mirror row_mask:0xf bank_mask:0xf bound_ctrl:1
	ds_read_b128 v[36:39], v172 offset:256
	ds_read_b128 v[40:43], v172 offset:16640
	v_add_f32_dpp v168, v168, v168 row_mirror row_mask:0xf bank_mask:0xf bound_ctrl:1
	v_fma_f32 v170, -v108, v168, v104
	v_mul_f32_e32 v170, v109, v170
	v_pk_fma_f32 v[10:11], v[76:77], v[170:171], v[160:161] op_sel_hi:[1,0,1]
	v_pk_fma_f32 v[12:13], v[78:79], v[170:171], v[162:163] op_sel_hi:[1,0,1]
	v_pk_mul_f32 v[158:159], v[10:11], v[84:85]
	v_pk_mul_f32 v[160:161], v[10:11], v[110:111] op_sel_hi:[1,0]
	v_pk_fma_f32 v[158:159], v[12:13], v[86:87], v[158:159]
	v_pk_mul_f32 v[162:163], v[12:13], v[110:111] op_sel_hi:[1,0]
	v_add_f32_e32 v168, v158, v159
	v_pk_mul_f32 v[164:165], v[72:73], v[10:11]
	ds_read_b128 v[44:47], v172 offset:512
	v_add_f32_dpp v168, v168, v168 quad_perm:[1,0,3,2] row_mask:0xf bank_mask:0xf bound_ctrl:1
	v_pk_fma_f32 v[164:165], v[74:75], v[12:13], v[164:165]
	ds_read_b128 v[48:51], v172 offset:16896
	v_add_f32_dpp v168, v168, v168 quad_perm:[2,3,0,1] row_mask:0xf bank_mask:0xf bound_ctrl:1
	v_add_f32_e32 v128, v164, v165
	ds_read_b128 v[52:55], v172 offset:768
	v_add_f32_dpp v168, v168, v168 row_half_mirror row_mask:0xf bank_mask:0xf bound_ctrl:1
	ds_read_b128 v[56:59], v172 offset:17152
	ds_read2_b32 v[60:61], v173 offset1:32
	v_add_f32_dpp v168, v168, v168 row_mirror row_mask:0xf bank_mask:0xf bound_ctrl:1
	v_fma_f32 v170, -v110, v168, v105
	v_mul_f32_e32 v170, v111, v170
	v_pk_fma_f32 v[10:11], v[84:85], v[170:171], v[160:161] op_sel_hi:[1,0,1]
	v_pk_fma_f32 v[12:13], v[86:87], v[170:171], v[162:163] op_sel_hi:[1,0,1]
	v_pk_mul_f32 v[158:159], v[10:11], v[92:93]
	v_pk_mul_f32 v[160:161], v[10:11], v[112:113] op_sel_hi:[1,0]
	v_pk_fma_f32 v[158:159], v[12:13], v[94:95], v[158:159]
	v_pk_mul_f32 v[162:163], v[12:13], v[112:113] op_sel_hi:[1,0]
	v_add_f32_e32 v168, v158, v159
	v_pk_mul_f32 v[166:167], v[80:81], v[10:11]
	ds_read2_b32 v[62:63], v173 offset0:64 offset1:96
	v_add_f32_dpp v168, v168, v168 quad_perm:[1,0,3,2] row_mask:0xf bank_mask:0xf bound_ctrl:1
	v_pk_fma_f32 v[166:167], v[82:83], v[12:13], v[166:167]
	ds_read2_b64 v[64:67], v174 offset1:2
	v_add_f32_dpp v168, v168, v168 quad_perm:[2,3,0,1] row_mask:0xf bank_mask:0xf bound_ctrl:1
	v_add_f32_e32 v129, v166, v167
	ds_read2_b64 v[68:71], v174 offset0:4 offset1:6
	v_add_f32_dpp v168, v168, v168 row_half_mirror row_mask:0xf bank_mask:0xf bound_ctrl:1
	v_add_u32_e32 v172, 0x400, v172
	v_add_u32_e32 v173, 0x200, v173
	v_add_f32_dpp v168, v168, v168 row_mirror row_mask:0xf bank_mask:0xf bound_ctrl:1
	v_fma_f32 v170, -v112, v168, v106
	v_mul_f32_e32 v170, v113, v170
	v_pk_fma_f32 v[10:11], v[92:93], v[170:171], v[160:161] op_sel_hi:[1,0,1]
	v_pk_fma_f32 v[12:13], v[94:95], v[170:171], v[162:163] op_sel_hi:[1,0,1]
	v_pk_mul_f32 v[158:159], v[10:11], v[100:101]
	v_pk_mul_f32 v[160:161], v[10:11], v[114:115] op_sel_hi:[1,0]
	v_pk_fma_f32 v[158:159], v[12:13], v[102:103], v[158:159]
	v_pk_mul_f32 v[162:163], v[12:13], v[114:115] op_sel_hi:[1,0]
	v_add_f32_e32 v168, v158, v159
	v_pk_mul_f32 v[164:165], v[88:89], v[10:11]
	v_add_u32_e32 v174, 64, v174
	v_add_f32_dpp v168, v168, v168 quad_perm:[1,0,3,2] row_mask:0xf bank_mask:0xf bound_ctrl:1
	v_pk_fma_f32 v[164:165], v[90:91], v[12:13], v[164:165]
	v_add_f32_dpp v146, v128, v128 row_mirror row_mask:0xf bank_mask:0x3 bound_ctrl:1
	v_add_f32_dpp v168, v168, v168 quad_perm:[2,3,0,1] row_mask:0xf bank_mask:0xf bound_ctrl:1
	v_add_f32_e32 v130, v164, v165
	v_add_f32_dpp v146, v129, v129 row_mirror row_mask:0xf bank_mask:0xc bound_ctrl:1
	v_add_f32_dpp v168, v168, v168 row_half_mirror row_mask:0xf bank_mask:0xf bound_ctrl:1
	v_add_f32_dpp v147, v130, v130 row_mirror row_mask:0xf bank_mask:0x3 bound_ctrl:1
	v_add_f32_dpp v149, v143, v143 row_half_mirror row_mask:0xf bank_mask:0xa bound_ctrl:1
	v_add_f32_dpp v168, v168, v168 row_mirror row_mask:0xf bank_mask:0xf bound_ctrl:1
	v_fma_f32 v170, -v114, v168, v107
	v_mul_f32_e32 v170, v115, v170
	v_pk_fma_f32 v[10:11], v[100:101], v[170:171], v[160:161] op_sel_hi:[1,0,1]
	v_pk_fma_f32 v[12:13], v[102:103], v[170:171], v[162:163] op_sel_hi:[1,0,1]
	v_pk_mul_f32 v[166:167], v[96:97], v[10:11]
	v_cndmask_b32_e64 v154, v149, v148, s[48:49]
	v_pk_fma_f32 v[166:167], v[98:99], v[12:13], v[166:167]
	v_cndmask_b32_e64 v155, v148, v149, s[48:49]
	v_add_f32_e32 v131, v166, v167
	v_add_f32_dpp v145, v127, v127 row_mirror row_mask:0xf bank_mask:0xc bound_ctrl:1
	v_add_f32_dpp v150, v144, v144 row_half_mirror row_mask:0xf bank_mask:0x5 bound_ctrl:1
	v_add_f32_dpp v147, v131, v131 row_mirror row_mask:0xf bank_mask:0xc bound_ctrl:1
	v_add_f32_dpp v151, v146, v146 row_half_mirror row_mask:0xf bank_mask:0x5 bound_ctrl:1
	v_add_f32_dpp v152, v155, v154 quad_perm:[3,2,1,0] row_mask:0xf bank_mask:0xf bound_ctrl:1
	v_add_f32_dpp v150, v145, v145 row_half_mirror row_mask:0xf bank_mask:0xa bound_ctrl:1
	v_add_f32_dpp v151, v147, v147 row_half_mirror row_mask:0xf bank_mask:0xa bound_ctrl:1
	v_cndmask_b32_e64 v154, v151, v150, s[48:49]
	v_cndmask_b32_e64 v155, v150, v151, s[48:49]
	s_nop 1
	v_add_f32_dpp v153, v155, v154 quad_perm:[3,2,1,0] row_mask:0xf bank_mask:0xf bound_ctrl:1
	v_cndmask_b32_e64 v154, v153, v152, s[50:51]
	v_cndmask_b32_e64 v155, v152, v153, s[50:51]
	s_nop 1
	v_add_f32_dpp v156, v155, v154 quad_perm:[1,0,3,2] row_mask:0xf bank_mask:0xf bound_ctrl:1
	ds_write_b32 v175, v156
	v_add_u32_e32 v175, 0x800, v175
	s_cmp_eq_u32 s8, 0
	s_cbranch_scc0 .Lgdn_step_loop
	s_waitcnt lgkmcnt(0)

; #define LAS __attribute__((address_space(3)))
; __device__ __forceinline__ void convert_tiles(int t0, int t1, int step, LAS float* tile) {
;     int t = t0;
;     if (t < t1) {
;         TileJob cur = tile_job(t); f32x4 v[2]; tile_load(cur, v);
;         for (;;) {
;             const int tn = t + step; const bool more = tn < t1;
;             TileJob nxt = cur; f32x4 vn[2];
;             if (more) { nxt = tile_job(tn); tile_load(nxt, vn); }
;             tile_store(cur, v, tile);
;             if (!more) break;
;             cur = nxt; v[0] = vn[0]; v[1] = vn[1]; t = tn;
;         }
;     }
; }
.LBB0_996:
	v_readlane_b32 s52, v252, 34
	v_readlane_b32 s54, v252, 36
	v_readlane_b32 s56, v252, 38
	v_readlane_b32 s58, v252, 40
	v_readlane_b32 s70, v252, 42
	v_readlane_b32 s74, v252, 44
	v_readlane_b32 s34, v252, 31
	s_mov_b64 s[4:5], 0
	v_readlane_b32 s53, v252, 35
	v_readlane_b32 s55, v252, 37
	v_readlane_b32 s57, v252, 39
	v_readlane_b32 s59, v252, 41
	v_readlane_b32 s71, v252, 43
	v_readlane_b32 s75, v252, 45
	v_readlane_b32 s35, v252, 32
	s_cmpk_lg_u32 s82, 0x100
	s_cbranch_scc1 .Lcvt_none
	s_cmp_eq_u32 s27, 1
	s_cbranch_scc1 .Lcvt_w1
	s_cmp_eq_u32 s27, 7
	s_cbranch_scc1 .Lcvt_w7
	s_cmp_eq_u32 s27, 10
	s_cbranch_scc1 .Lcvt_w10
	s_cmp_eq_u32 s27, 16
	s_cbranch_scc0 .Lcvt_none
	s_sub_u32 s40, s17, 32
	s_cbranch_scc1 .Lcvt_none
	s_mul_i32 s40, s40, 5
	s_add_u32 s40, s40, 0x1680
	s_add_u32 s41, s40, 5
	s_min_u32 s41, s41, 0x1a80
	s_branch .Lcvt_go

; __device__ __forceinline__ int tidx() { int t = threadIdx.x; asm volatile("" : "+v"(t)); return t; }
; __device__ __forceinline__ const float* pin(int i) { return kargs()->in[i]; }
; __device__ __forceinline__ unsigned char* pws() { return kargs()->ws; }
; __device__ __forceinline__ TileJob tile_job(int t) {
;     constexpr int n_in = 16 * (PN / 64), n_out = 16 * 16, n_up = 16 * 64, n_dn = 64 * 16, tot = n_in + n_out + n_up + n_dn;
;     const int l = t >= tot ? 1 : 0, u0 = t - l * tot;
;     f16_t* wt = (f16_t*)(pws() + WS_WT + l * WT_LAYER);
;     TileJob j;
;     if (u0 < n_in) { j = TileJob{pin(9) + (size_t)l * DM * PTOT, wt + WT_WIN / 2, DM, PTOT, u0 % 16, u0 / 16}; }
;     else if (u0 < n_in + n_out) { const int u = u0 - n_in; j = TileJob{pin(22) + (size_t)l * DM * DM, wt + WT_WOUT / 2, DM, DM, u % 16, u / 16}; }
;     else if (u0 < n_in + n_out + n_up) { const int u = u0 - n_in - n_out; j = TileJob{pin(24) + (size_t)l * DM * DFF, wt + WT_WUP / 2, DM, DFF, u % 16, u / 16}; }
;     else { const int u = u0 - n_in - n_out - n_up; j = TileJob{pin(25) + (size_t)l * DFF * DM, wt + WT_WDOWN / 2, DFF, DM, u % 64, u / 64}; }
;     return j;
; }
; __device__ __forceinline__ void tile_load(const TileJob& j, f32x4 (&v)[2]) {
;     const int tid = tidx(), k0 = j.tk * 64, n0 = j.tn * 64;
; #pragma unroll
;     for (int i = 0; i < 2; ++i) { const int r = (tid >> 4) + 32 * i, c = (tid & 15) * 4, n = n0 + c;
;         v[i] = (f32x4){0.f, 0.f, 0.f, 0.f};
;         if (n < j.Nreal) v[i] = *(const f32x4*)(j.W + (size_t)(k0 + r) * j.Nreal + n); }
; }
.Lcvt_go:
	s_cmp_ge_u32 s40, s41
	s_cbranch_scc1 .Lcvt_none
	s_load_dwordx2 s[2:3], s[0:1], 0x48
	s_load_dwordx2 s[6:7], s[0:1], 0xb0
	s_load_dwordx2 s[8:9], s[0:1], 0xc0
	s_load_dwordx2 s[10:11], s[0:1], 0xc8
	s_load_dwordx2 s[12:13], s[0:1], 0xe0
	v_lshrrev_b32_e32 v1, 4, v202
	v_and_b32_e32 v3, 15, v202
	v_lshlrev_b32_e32 v3, 2, v3
	v_lshlrev_b32_e32 v2, 2, v3
	v_lshrrev_b32_e32 v4, 3, v202
	v_and_b32_e32 v8, 7, v202
	v_lshlrev_b32_e32 v5, 4, v8
	v_lshlrev_b32_e32 v8, 3, v8
	s_movk_i32 s22, 0x104
	v_mad_u32_u24 v6, v1, s22, v2
	v_lshlrev_b32_e32 v9, 2, v4
	v_mad_u32_u24 v7, v8, s22, v9
	v_add_u32_e32 v10, 0x2080, v6
	v_add_u32_e32 v11, 0x410, v7
	s_waitcnt lgkmcnt(0)
	v_writelane_b32 v12, s2, 0
	v_writelane_b32 v12, s3, 1
	v_writelane_b32 v12, s6, 2
	v_writelane_b32 v12, s7, 3
	v_writelane_b32 v12, s8, 4
	v_writelane_b32 v12, s9, 5
	v_writelane_b32 v12, s10, 6
	v_writelane_b32 v12, s11, 7
	s_mov_b32 s26, s40
	s_sub_u32 s9, s41, 1
	s_min_u32 s26, s26, s9
	s_cmp_ge_u32 s26, 0xd40
	s_cselect_b32 s36, 1, 0
	s_cselect_b32 s30, 0xd40, 0
	s_sub_u32 s30, s26, s30
	s_movk_i32 s31, 6
	s_mov_b32 s2, 0x1000000
	s_movk_i32 s3, 0x400
	s_movk_i32 s6, 0x940
	s_mov_b32 s7, 0x1280000
	s_cmp_lt_u32 s30, 0x940
	s_cselect_b32 s31, 4, s31
	s_cselect_b32 s3, 0x1000, s3
	s_cselect_b32 s6, 0x540, s6
	s_cselect_b32 s7, 0xa80000, s7
	s_cselect_b32 s8, 0, 1
	s_cmp_lt_u32 s30, 0x540
	s_cselect_b32 s31, 2, s31
	s_cselect_b32 s2, 0x400000, s2
	s_cselect_b32 s3, 0x400, s3
	s_cselect_b32 s6, 0x440, s6
	s_cselect_b32 s7, 0x880000, s7
	s_cmp_lt_u32 s30, 0x440
	s_cselect_b32 s31, 0, s31
	s_cselect_b32 s2, 0x100c000, s2
	s_cselect_b32 s3, 0x100c, s3
	s_cselect_b32 s6, 0, s6
	s_cselect_b32 s7, 0, s7
	s_sub_u32 s30, s30, s6
	s_cmp_eq_u32 s8, 1
	s_movk_i32 s22, 0x800
	s_cselect_b32 s22, 0x2000, s22
	s_cmp_eq_u32 s31, 4
	s_cselect_b32 s9, 6, 4
	s_cselect_b32 s10, 63, 15
	s_lshr_b32 s11, s30, s9
	s_and_b32 s10, s30, s10
	s_mul_hi_u32 s9, s30, 0x3c3c3c4
	s_mul_i32 s6, s9, 68
	s_sub_u32 s6, s30, s6
	s_cmp_eq_u32 s31, 0
	s_cselect_b32 s11, s9, s11
	s_cselect_b32 s10, s6, s10
	s_mov_b32 s9, s11
	s_mov_b32 s11, s10
	s_mov_b32 s10, s9
	v_readlane_b32 s4, v12, s31
	s_add_u32 s31, s31, 1
	v_readlane_b32 s5, v12, s31
	s_mul_i32 s2, s2, s36
	s_lshl_b32 s9, s3, 2
	s_mul_i32 s8, s10, s9
	s_lshl_b32 s8, s8, 6
	s_add_u32 s2, s2, s8
	s_add_u32 s4, s4, s2
	s_addc_u32 s5, s5, 0
	s_mul_i32 s2, s11, s22
	s_lshl_b32 s2, s2, 6
	s_lshl_b32 s8, s10, 7
	s_add_u32 s2, s2, s8
	s_add_u32 s2, s2, s7
	s_mul_i32 s8, s36, 0x1a80000
	s_add_u32 s2, s2, s8
	s_add_u32 s42, s12, s2
	s_addc_u32 s43, s13, 0
	s_lshl_b32 s8, s11, 6
	s_sub_i32 s2, s3, s8
	v_cmp_gt_i32_e64 s[48:49], s2, v3
	s_lshl_b32 s8, s8, 2
	v_add_u32_e32 v13, s8, v2
	s_lshl_b32 s8, s9, 5
	s_add_u32 s6, s4, s8
	s_addc_u32 s7, s5, 0
	v_cndmask_b32_e64 v13, 0, v13, s[48:49]
	v_mad_u32_u24 v13, v1, s9, v13
	global_load_dwordx4 v[20:23], v13, s[4:5]
	global_load_dwordx4 v[24:27], v13, s[6:7]
	s_add_u32 s26, s40, 1
	s_sub_u32 s9, s41, 1
	s_min_u32 s26, s26, s9
	s_cmp_ge_u32 s26, 0xd40
	s_cselect_b32 s36, 1, 0
	s_cselect_b32 s30, 0xd40, 0
	s_sub_u32 s30, s26, s30
	s_movk_i32 s31, 6
	s_mov_b32 s2, 0x1000000
	s_movk_i32 s3, 0x400
	s_movk_i32 s6, 0x940
	s_mov_b32 s7, 0x1280000
	s_cmp_lt_u32 s30, 0x940
	s_cselect_b32 s31, 4, s31
	s_cselect_b32 s3, 0x1000, s3
	s_cselect_b32 s6, 0x540, s6
	s_cselect_b32 s7, 0xa80000, s7
	s_cselect_b32 s8, 0, 1
	s_cmp_lt_u32 s30, 0x540
	s_cselect_b32 s31, 2, s31
	s_cselect_b32 s2, 0x400000, s2
	s_cselect_b32 s3, 0x400, s3
	s_cselect_b32 s6, 0x440, s6
	s_cselect_b32 s7, 0x880000, s7
	s_cmp_lt_u32 s30, 0x440
	s_cselect_b32 s31, 0, s31
	s_cselect_b32 s2, 0x100c000, s2
	s_cselect_b32 s3, 0x100c, s3
	s_cselect_b32 s6, 0, s6
	s_cselect_b32 s7, 0, s7
	s_sub_u32 s30, s30, s6
	s_cmp_eq_u32 s8, 1
	s_movk_i32 s23, 0x800
	s_cselect_b32 s23, 0x2000, s23
	s_cmp_eq_u32 s31, 4
	s_cselect_b32 s9, 6, 4
	s_cselect_b32 s10, 63, 15
	s_lshr_b32 s11, s30, s9
	s_and_b32 s10, s30, s10
	s_mul_hi_u32 s9, s30, 0x3c3c3c4
	s_mul_i32 s6, s9, 68
	s_sub_u32 s6, s30, s6
	s_cmp_eq_u32 s31, 0
	s_cselect_b32 s11, s9, s11
	s_cselect_b32 s10, s6, s10
	s_mov_b32 s9, s11
	s_mov_b32 s11, s10
	s_mov_b32 s10, s9
	v_readlane_b32 s4, v12, s31
	s_add_u32 s31, s31, 1
	v_readlane_b32 s5, v12, s31
	s_mul_i32 s2, s2, s36
	s_lshl_b32 s9, s3, 2
	s_mul_i32 s8, s10, s9
	s_lshl_b32 s8, s8, 6
	s_add_u32 s2, s2, s8
	s_add_u32 s4, s4, s2
	s_addc_u32 s5, s5, 0
	s_mul_i32 s2, s11, s23
	s_lshl_b32 s2, s2, 6
	s_lshl_b32 s8, s10, 7
	s_add_u32 s2, s2, s8
	s_add_u32 s2, s2, s7
	s_mul_i32 s8, s36, 0x1a80000
	s_add_u32 s2, s2, s8
	s_add_u32 s44, s12, s2
	s_addc_u32 s45, s13, 0
	s_lshl_b32 s8, s11, 6
	s_sub_i32 s2, s3, s8
	v_cmp_gt_i32_e64 s[50:51], s2, v3
	s_lshl_b32 s8, s8, 2
	v_add_u32_e32 v13, s8, v2
	s_lshl_b32 s8, s9, 5
	s_add_u32 s6, s4, s8
	s_addc_u32 s7, s5, 0
	v_cndmask_b32_e64 v13, 0, v13, s[50:51]
	v_mad_u32_u24 v13, v1, s9, v13
	global_load_dwordx4 v[28:31], v13, s[4:5]
	global_load_dwordx4 v[32:35], v13, s[6:7]
; __device__ __forceinline__ TileJob tile_job(int t) {
;     constexpr int n_in = 16 * (PN / 64), n_out = 16 * 16, n_up = 16 * 64, n_dn = 64 * 16, tot = n_in + n_out + n_up + n_dn;
;     const int l = t >= tot ? 1 : 0, u0 = t - l * tot;
;     f16_t* wt = (f16_t*)(pws() + WS_WT + l * WT_LAYER);
;     TileJob j;
;     if (u0 < n_in) { j = TileJob{pin(9) + (size_t)l * DM * PTOT, wt + WT_WIN / 2, DM, PTOT, u0 % 16, u0 / 16}; }
;     else if (u0 < n_in + n_out) { const int u = u0 - n_in; j = TileJob{pin(22) + (size_t)l * DM * DM, wt + WT_WOUT / 2, DM, DM, u % 16, u / 16}; }
;     else if (u0 < n_in + n_out + n_up) { const int u = u0 - n_in - n_out; j = TileJob{pin(24) + (size_t)l * DM * DFF, wt + WT_WUP / 2, DM, DFF, u % 16, u / 16}; }
;     else { const int u = u0 - n_in - n_out - n_up; j = TileJob{pin(25) + (size_t)l * DFF * DM, wt + WT_WDOWN / 2, DFF, DM, u % 64, u / 64}; }
;     return j;
; }
; __device__ __forceinline__ void tile_load(const TileJob& j, f32x4 (&v)[2]) {
;     const int tid = tidx(), k0 = j.tk * 64, n0 = j.tn * 64;
; #pragma unroll
;     for (int i = 0; i < 2; ++i) { const int r = (tid >> 4) + 32 * i, c = (tid & 15) * 4, n = n0 + c;
;         v[i] = (f32x4){0.f, 0.f, 0.f, 0.f};
;         if (n < j.Nreal) v[i] = *(const f32x4*)(j.W + (size_t)(k0 + r) * j.Nreal + n); }
; }
; __device__ __forceinline__ void tile_store(const TileJob& j, const f32x4 (&v)[2], LAS float* tile) {
;     const int tid = tidx(), k0 = j.tk * 64, n0 = j.tn * 64;
; #pragma unroll
;     for (int i = 0; i < 2; ++i) { const int r = (tid >> 4) + 32 * i, c = (tid & 15) * 4;
;         tile[r * 65 + c] = v[i][0]; tile[r * 65 + c + 1] = v[i][1]; tile[r * 65 + c + 2] = v[i][2]; tile[r * 65 + c + 3] = v[i][3]; }
;     __syncthreads();
;     { const int nl = tid >> 3, k8 = (tid & 7) * 8; u32x4 w;
;       w.x = pkh(tile[(k8 + 0) * 65 + nl], tile[(k8 + 1) * 65 + nl]); w.y = pkh(tile[(k8 + 2) * 65 + nl], tile[(k8 + 3) * 65 + nl]);
;       w.z = pkh(tile[(k8 + 4) * 65 + nl], tile[(k8 + 5) * 65 + nl]); w.w = pkh(tile[(k8 + 6) * 65 + nl], tile[(k8 + 7) * 65 + nl]);
;       *(u32x4*)(j.Bt + (size_t)(n0 + nl) * j.Kdim + k0 + k8) = w; }
;     __syncthreads();
; }
; __device__ __forceinline__ void convert_tiles(int t0, int t1, int step, LAS float* tile) {
;     int t = t0;
;     if (t < t1) {
;         TileJob cur = tile_job(t); f32x4 v[2]; tile_load(cur, v);
;         for (;;) {
.Lcvt_loop:
	s_waitcnt vmcnt(0)
	v_cndmask_b32_e64 v20, 0, v20, s[48:49]
	v_cndmask_b32_e64 v21, 0, v21, s[48:49]
	v_cndmask_b32_e64 v22, 0, v22, s[48:49]
	v_cndmask_b32_e64 v23, 0, v23, s[48:49]
	v_cndmask_b32_e64 v24, 0, v24, s[48:49]
	v_cndmask_b32_e64 v25, 0, v25, s[48:49]
	v_cndmask_b32_e64 v26, 0, v26, s[48:49]
	v_cndmask_b32_e64 v27, 0, v27, s[48:49]
	ds_write2_b32 v6, v20, v21 offset1:1
	ds_write2_b32 v6, v22, v23 offset0:2 offset1:3
	ds_write2_b32 v10, v24, v25 offset1:1
	ds_write2_b32 v10, v26, v27 offset0:2 offset1:3
	s_waitcnt lgkmcnt(0)
	s_barrier
	ds_read2_b32 v[14:15], v7 offset1:65
	ds_read2_b32 v[18:19], v7 offset0:130 offset1:195
	ds_read2_b32 v[44:45], v11 offset1:65
	ds_read2_b32 v[46:47], v11 offset0:130 offset1:195
	v_mad_u32_u24 v48, v4, s22, v5
	s_waitcnt lgkmcnt(0)
	v_cvt_pk_f16_f32 v50, v14, v15
	v_cvt_pk_f16_f32 v51, v18, v19
	v_cvt_pk_f16_f32 v52, v44, v45
	v_cvt_pk_f16_f32 v53, v46, v47
	global_store_dwordx4 v48, v[50:53], s[42:43]
	s_add_u32 s26, s40, 1
	s_sub_u32 s9, s41, 1
	s_min_u32 s26, s26, s9
	s_cmp_ge_u32 s26, 0xd40
	s_cselect_b32 s36, 1, 0
	s_cselect_b32 s30, 0xd40, 0
	s_sub_u32 s30, s26, s30
	s_movk_i32 s31, 6
	s_mov_b32 s2, 0x1000000
	s_movk_i32 s3, 0x400
	s_movk_i32 s6, 0x940
	s_mov_b32 s7, 0x1280000
	s_cmp_lt_u32 s30, 0x940
	s_cselect_b32 s31, 4, s31
	s_cselect_b32 s3, 0x1000, s3
	s_cselect_b32 s6, 0x540, s6
	s_cselect_b32 s7, 0xa80000, s7
	s_cselect_b32 s8, 0, 1
	s_cmp_lt_u32 s30, 0x540
	s_cselect_b32 s31, 2, s31
	s_cselect_b32 s2, 0x400000, s2
	s_cselect_b32 s3, 0x400, s3
	s_cselect_b32 s6, 0x440, s6
	s_cselect_b32 s7, 0x880000, s7
	s_cmp_lt_u32 s30, 0x440
	s_cselect_b32 s31, 0, s31
	s_cselect_b32 s2, 0x100c000, s2
	s_cselect_b32 s3, 0x100c, s3
	s_cselect_b32 s6, 0, s6
	s_cselect_b32 s7, 0, s7
	s_sub_u32 s30, s30, s6
	s_cmp_eq_u32 s8, 1
	s_movk_i32 s22, 0x800
	s_cselect_b32 s22, 0x2000, s22
	s_cmp_eq_u32 s31, 4
	s_cselect_b32 s9, 6, 4
	s_cselect_b32 s10, 63, 15
	s_lshr_b32 s11, s30, s9
	s_and_b32 s10, s30, s10
	s_mul_hi_u32 s9, s30, 0x3c3c3c4
	s_mul_i32 s6, s9, 68
	s_sub_u32 s6, s30, s6
	s_cmp_eq_u32 s31, 0
	s_cselect_b32 s11, s9, s11
	s_cselect_b32 s10, s6, s10
	s_mov_b32 s9, s11
	s_mov_b32 s11, s10
	s_mov_b32 s10, s9
	v_readlane_b32 s4, v12, s31
	s_add_u32 s31, s31, 1
	v_readlane_b32 s5, v12, s31
	s_mul_i32 s2, s2, s36
	s_lshl_b32 s9, s3, 2
	s_mul_i32 s8, s10, s9
	s_lshl_b32 s8, s8, 6
	s_add_u32 s2, s2, s8
	s_add_u32 s4, s4, s2
	s_addc_u32 s5, s5, 0
	s_mul_i32 s2, s11, s22
	s_lshl_b32 s2, s2, 6
	s_lshl_b32 s8, s10, 7
	s_add_u32 s2, s2, s8
	s_add_u32 s2, s2, s7
	s_mul_i32 s8, s36, 0x1a80000
	s_add_u32 s2, s2, s8
	s_add_u32 s42, s12, s2
	s_addc_u32 s43, s13, 0
	s_lshl_b32 s8, s11, 6
	s_sub_i32 s2, s3, s8
	v_cmp_gt_i32_e64 s[48:49], s2, v3
	s_lshl_b32 s8, s8, 2
	v_add_u32_e32 v13, s8, v2
	s_lshl_b32 s8, s9, 5
	s_add_u32 s6, s4, s8
	s_addc_u32 s7, s5, 0
	v_cndmask_b32_e64 v13, 0, v13, s[48:49]
	v_mad_u32_u24 v13, v1, s9, v13
	global_load_dwordx4 v[20:23], v13, s[4:5]
	global_load_dwordx4 v[24:27], v13, s[6:7]
	s_barrier
	s_add_u32 s40, s40, 1
	s_cmp_ge_u32 s40, s41
	s_cbranch_scc1 .Lcvt_end
	s_branch .Lcvt_loop
